# on top of v145: GEMM0 K-loop LDS-DMA tile loads use SGPR base + 32-bit VGPR offset (12 of 16 per iteration), their 64-bit VALU address adds deleted
# baseline (speedup 1.0000x reference)
; #define PG8_STAGE(bufoff, gbase, voff) do { _Pragma("unroll") for (int _i = 0; _i < 2; ++_i) \
;         __builtin_amdgcn_global_load_lds((const unsigned*)((const char*)(gbase) + (voff)[_i]), (PG8_LAS unsigned*)(lds + (bufoff) + ldsw + _i * 8192), 16, 0, 0); } while (0)
; #define PG8_LDA(dst, b, h) do { _Pragma("unroll") for (int m = 0; m < 4; ++m) _Pragma("unroll") for (int k = 0; k < 2; ++k) dst[m][k] = *(const PG8_LAS bf16x8*)(lds + PG8_SA(b, h) + aoff + m * 2048 + k * 1024); } while (0)
; #define PG8_LDB(dst, b, h) do { _Pragma("unroll") for (int n = 0; n < 2; ++n) _Pragma("unroll") for (int k = 0; k < 2; ++k) dst[n][k] = *(const PG8_LAS bf16x8*)(lds + PG8_SB(b, h) + boff + n * 2048 + k * 1024); } while (0)
; #define PG8_WAIT_V(n) asm volatile("s_waitcnt vmcnt(" #n ")" ::: "memory")
; #define PG8_WAIT_L(n) asm volatile("s_waitcnt lgkmcnt(" #n ")" ::: "memory")
; #define PG8_BAR __builtin_amdgcn_s_barrier()
; #define PG8_SCHED __builtin_amdgcn_sched_barrier(0)
; template <class Epi, class Sched, bool ALIGN_EPI = false, bool SP2 = false>
; __device__ __forceinline__ void gemm_phase(PG8_LAS unsigned char* lds, const Gemm g, const Sched& S, const Epi& E) {
;     ...
;     for (;;) {
;         const bool has_next = S.next(ui + 1, nxt);
;         const char* nA = has_next ? (const char*)g.A + (size_t)nxt.pm * tstep : cA; const char* nB = has_next ? (const char*)g.Bt + (size_t)nxt.pn * tstep : cB;
;         for (int t = 0; t < nt; t += 2) {
;             const bool last = (t == nt - 2);
;             const char* a1 = cA + (size_t)(t + 1) * kstep;
;             const char* a2 = last ? nA : cA + (size_t)(t + 2) * kstep; const char* b2 = last ? nB : cB + (size_t)(t + 2) * kstep;
;             const char* a3 = a2 + kstep; const char* b3 = b2 + kstep;
;             if (last && has_next) S.a_ready(nxt);
;             if constexpr (SP2) {
;             PG8_LDB(B0, 0, 0); PG8_LDB(B1, 0, 1); PG8_SCHED; PG8_LDA(At, 0, 0); PG8_STAGE(PG8_SA(1, 1), a1 + hstep, voffA);
;             PG8_WAIT_V(8); PG8_WAIT_L(0); PG8_BAR; PG8_MMA(0, 0, At, B0); PG8_MMA(0, 1, At, B1); PG8_BAR; PG8_SCHED;
;             PG8_LDA(At, 0, 1); PG8_STAGE(PG8_SB(0, 0), b2, voffB); PG8_STAGE(PG8_SB(0, 1), b2 + hstep, voffB); PG8_STAGE(PG8_SA(0, 0), a2, voffA);
;             PG8_WAIT_V(8); PG8_WAIT_L(0); PG8_BAR; PG8_MMA(1, 0, At, B0); PG8_MMA(1, 1, At, B1); PG8_BAR; PG8_SCHED;
.LBB0_116:
	s_add_u32 s2, s0, 0xfffc0080
	s_addc_u32 s3, s1, -1
	s_add_i32 s43, 0, 0x10000
	s_cmp_eq_u32 s42, 12
	s_cselect_b32 s9, s11, s3
	s_cselect_b32 s8, s12, s2
	s_cselect_b32 s3, s13, s33
	s_cselect_b32 s2, s19, s21
	s_add_i32 s46, 0, 0x14000
	v_add_u32_e32 v140, s43, v182
	v_add_u32_e32 v152, s46, v182
	ds_read_b128 v[128:131], v140
	ds_read_b128 v[132:135], v140 offset:1024
	ds_read_b128 v[136:139], v140 offset:2048
	ds_read_b128 v[140:143], v140 offset:3072
	ds_read_b128 v[174:177], v152
	ds_read_b128 v[178:181], v152 offset:1024
	ds_read_b128 v[186:189], v152 offset:2048
	ds_read_b128 v[190:193], v152 offset:3072
	s_add_i32 m0, s29, 0xc000
	ds_read_b128 v[194:197], v185
	ds_read_b128 v[198:201], v185 offset:1024
	ds_read_b128 v[202:205], v185 offset:2048
	ds_read_b128 v[206:209], v185 offset:3072
	ds_read_b128 v[210:213], v185 offset:4096
	ds_read_b128 v[214:217], v185 offset:5120
	ds_read_b128 v[218:221], v185 offset:6144
	ds_read_b128 v[222:225], v185 offset:7168
	global_load_lds_dwordx4 v170, s[0:1]
	s_add_i32 m0, s29, 0xe000
	s_nop 0
	global_load_lds_dwordx4 v172, s[0:1]
	s_waitcnt vmcnt(8)
	s_waitcnt lgkmcnt(0)
	s_barrier
	s_setprio 1
	s_waitcnt lgkmcnt(0)
	v_mfma_f32_16x16x32_bf16 v[124:127], v[128:131], v[194:197], v[124:127]
	v_mfma_f32_16x16x32_bf16 v[120:123], v[136:139], v[194:197], v[120:123]
	v_mfma_f32_16x16x32_bf16 v[108:111], v[128:131], v[202:205], v[108:111]
	v_mfma_f32_16x16x32_bf16 v[104:107], v[136:139], v[202:205], v[104:107]
	v_mfma_f32_16x16x32_bf16 v[92:95], v[128:131], v[210:213], v[92:95]
	v_mfma_f32_16x16x32_bf16 v[88:91], v[136:139], v[210:213], v[88:91]
	v_mfma_f32_16x16x32_bf16 v[76:79], v[128:131], v[218:221], v[76:79]
	v_mfma_f32_16x16x32_bf16 v[72:75], v[136:139], v[218:221], v[72:75]
	v_mfma_f32_16x16x32_bf16 v[124:127], v[132:135], v[198:201], v[124:127]
	v_mfma_f32_16x16x32_bf16 v[120:123], v[140:143], v[198:201], v[120:123]
	v_mfma_f32_16x16x32_bf16 v[108:111], v[132:135], v[206:209], v[108:111]
	v_mfma_f32_16x16x32_bf16 v[104:107], v[140:143], v[206:209], v[104:107]
	v_mfma_f32_16x16x32_bf16 v[92:95], v[132:135], v[214:217], v[92:95]
	v_mfma_f32_16x16x32_bf16 v[88:91], v[140:143], v[214:217], v[88:91]
	v_mfma_f32_16x16x32_bf16 v[76:79], v[132:135], v[222:225], v[76:79]
	v_mfma_f32_16x16x32_bf16 v[72:75], v[140:143], v[222:225], v[72:75]
	s_setprio 0
	s_setprio 1
	v_mfma_f32_16x16x32_bf16 v[116:119], v[174:177], v[194:197], v[116:119]
	v_mfma_f32_16x16x32_bf16 v[112:115], v[186:189], v[194:197], v[112:115]
	v_mfma_f32_16x16x32_bf16 v[100:103], v[174:177], v[202:205], v[100:103]
	v_mfma_f32_16x16x32_bf16 v[96:99], v[186:189], v[202:205], v[96:99]
	v_mfma_f32_16x16x32_bf16 v[84:87], v[174:177], v[210:213], v[84:87]
	v_mfma_f32_16x16x32_bf16 v[80:83], v[186:189], v[210:213], v[80:83]
	v_mfma_f32_16x16x32_bf16 v[68:71], v[174:177], v[218:221], v[68:71]
	v_mfma_f32_16x16x32_bf16 v[64:67], v[186:189], v[218:221], v[64:67]
	v_mfma_f32_16x16x32_bf16 v[116:119], v[178:181], v[198:201], v[116:119]
	v_mfma_f32_16x16x32_bf16 v[112:115], v[190:193], v[198:201], v[112:115]
	v_mfma_f32_16x16x32_bf16 v[100:103], v[178:181], v[206:209], v[100:103]
	v_mfma_f32_16x16x32_bf16 v[96:99], v[190:193], v[206:209], v[96:99]
	v_mfma_f32_16x16x32_bf16 v[84:87], v[178:181], v[214:217], v[84:87]
	v_mfma_f32_16x16x32_bf16 v[80:83], v[190:193], v[214:217], v[80:83]
	v_mfma_f32_16x16x32_bf16 v[68:71], v[178:181], v[222:225], v[68:71]
	v_mfma_f32_16x16x32_bf16 v[64:67], v[190:193], v[222:225], v[64:67]
	s_setprio 0
	s_barrier
	s_add_i32 s43, s43, s28
	v_lshl_add_u64 v[226:227], s[2:3], 0, v[148:149]
	s_mov_b32 m0, s43
	ds_read_b128 v[194:197], v185 offset:16384
	ds_read_b128 v[198:201], v185 offset:17408
	ds_read_b128 v[202:205], v185 offset:18432
	ds_read_b128 v[206:209], v185 offset:19456
	ds_read_b128 v[210:213], v185 offset:20480
	ds_read_b128 v[214:217], v185 offset:21504
	ds_read_b128 v[218:221], v185 offset:22528
	ds_read_b128 v[222:225], v185 offset:23552
	global_load_lds_dwordx4 v148, s[2:3]
	s_add_i32 m0, s43, 0x2000
	s_add_u32 s44, s2, 0x40000
	v_lshl_add_u64 v[228:229], s[2:3], 0, v[144:145]
	s_addc_u32 s45, s3, 0
	s_add_i32 s43, s46, s28
	global_load_lds_dwordx4 v144, s[2:3]
	s_mov_b32 m0, s43
	v_lshl_add_u64 v[232:233], s[8:9], 0, v[146:147]
	global_load_lds_dwordx4 v148, s[44:45]
	s_add_i32 m0, s43, 0x2000
	s_nop 0
	global_load_lds_dwordx4 v144, s[44:45]
	v_lshl_add_u64 v[230:231], s[8:9], 0, v[150:151]
	s_mov_b32 m0, s29
	s_nop 0
	global_load_lds_dwordx4 v150, s[8:9]
	s_mov_b32 m0, s30
	s_nop 0
	global_load_lds_dwordx4 v146, s[8:9]
	s_waitcnt vmcnt(8)
	s_waitcnt lgkmcnt(0)
	s_barrier
; #define PG8_STAGE(bufoff, gbase, voff) do { _Pragma("unroll") for (int _i = 0; _i < 2; ++_i) \
;         __builtin_amdgcn_global_load_lds((const unsigned*)((const char*)(gbase) + (voff)[_i]), (PG8_LAS unsigned*)(lds + (bufoff) + ldsw + _i * 8192), 16, 0, 0); } while (0)
; #define PG8_LDA(dst, b, h) do { _Pragma("unroll") for (int m = 0; m < 4; ++m) _Pragma("unroll") for (int k = 0; k < 2; ++k) dst[m][k] = *(const PG8_LAS bf16x8*)(lds + PG8_SA(b, h) + aoff + m * 2048 + k * 1024); } while (0)
; #define PG8_LDB(dst, b, h) do { _Pragma("unroll") for (int n = 0; n < 2; ++n) _Pragma("unroll") for (int k = 0; k < 2; ++k) dst[n][k] = *(const PG8_LAS bf16x8*)(lds + PG8_SB(b, h) + boff + n * 2048 + k * 1024); } while (0)
; #define PG8_MMA(ai, bj, At, Bt) do { __builtin_amdgcn_s_setprio(1); _Pragma("unroll") for (int m = 0; m < 4; ++m) _Pragma("unroll") for (int n = 0; n < 2; ++n) _Pragma("unroll") for (int k = 0; k < 2; ++k) \
;         acc[ai][bj][m][n] = __builtin_amdgcn_mfma_f32_16x16x32_bf16(Bt[n][k], At[m][k], acc[ai][bj][m][n], 0, 0, 0); __builtin_amdgcn_s_setprio(0); } while (0)
; #define PG8_WAIT_V(n) asm volatile("s_waitcnt vmcnt(" #n ")" ::: "memory")
; #define PG8_WAIT_L(n) asm volatile("s_waitcnt lgkmcnt(" #n ")" ::: "memory")
; #define PG8_BAR __builtin_amdgcn_s_barrier()
; #define PG8_SCHED __builtin_amdgcn_sched_barrier(0)
; template <class Epi, class Sched, bool ALIGN_EPI = false, bool SP2 = false>
; __device__ __forceinline__ void gemm_phase(PG8_LAS unsigned char* lds, const Gemm g, const Sched& S, const Epi& E) {
;     ...
;             PG8_WAIT_V(8); PG8_WAIT_L(0); PG8_BAR; PG8_MMA(1, 0, At, B0); PG8_MMA(1, 1, At, B1); PG8_BAR; PG8_SCHED;
;             PG8_LDB(B0, 1, 0); PG8_LDB(B1, 1, 1); PG8_SCHED; PG8_LDA(At, 1, 0); PG8_STAGE(PG8_SA(0, 1), a2 + hstep, voffA);
;             PG8_WAIT_V(8); PG8_WAIT_L(0); PG8_BAR; PG8_MMA(0, 0, At, B0); PG8_MMA(0, 1, At, B1); PG8_BAR; PG8_SCHED;
	s_setprio 1
	s_waitcnt lgkmcnt(0)
	v_mfma_f32_16x16x32_bf16 v[60:63], v[128:131], v[194:197], v[60:63]
	v_mfma_f32_16x16x32_bf16 v[56:59], v[136:139], v[194:197], v[56:59]
	v_mfma_f32_16x16x32_bf16 v[44:47], v[128:131], v[202:205], v[44:47]
	v_mfma_f32_16x16x32_bf16 v[40:43], v[136:139], v[202:205], v[40:43]
	v_mfma_f32_16x16x32_bf16 v[28:31], v[128:131], v[210:213], v[28:31]
	v_mfma_f32_16x16x32_bf16 v[24:27], v[136:139], v[210:213], v[24:27]
	v_mfma_f32_16x16x32_bf16 v[12:15], v[128:131], v[218:221], v[12:15]
	v_mfma_f32_16x16x32_bf16 v[8:11], v[136:139], v[218:221], v[8:11]
	v_mfma_f32_16x16x32_bf16 v[60:63], v[132:135], v[198:201], v[60:63]
	v_mfma_f32_16x16x32_bf16 v[56:59], v[140:143], v[198:201], v[56:59]
	v_mfma_f32_16x16x32_bf16 v[44:47], v[132:135], v[206:209], v[44:47]
	v_mfma_f32_16x16x32_bf16 v[40:43], v[140:143], v[206:209], v[40:43]
	v_mfma_f32_16x16x32_bf16 v[28:31], v[132:135], v[214:217], v[28:31]
	v_mfma_f32_16x16x32_bf16 v[24:27], v[140:143], v[214:217], v[24:27]
	v_mfma_f32_16x16x32_bf16 v[12:15], v[132:135], v[222:225], v[12:15]
	v_mfma_f32_16x16x32_bf16 v[8:11], v[140:143], v[222:225], v[8:11]
	s_setprio 0
	s_setprio 1
	v_mfma_f32_16x16x32_bf16 v[52:55], v[174:177], v[194:197], v[52:55]
	v_mfma_f32_16x16x32_bf16 v[48:51], v[186:189], v[194:197], v[48:51]
	v_mfma_f32_16x16x32_bf16 v[36:39], v[174:177], v[202:205], v[36:39]
	v_mfma_f32_16x16x32_bf16 v[32:35], v[186:189], v[202:205], v[32:35]
	v_mfma_f32_16x16x32_bf16 v[20:23], v[174:177], v[210:213], v[20:23]
	v_mfma_f32_16x16x32_bf16 v[16:19], v[186:189], v[210:213], v[16:19]
	v_mfma_f32_16x16x32_bf16 v[4:7], v[174:177], v[218:221], v[4:7]
	v_mfma_f32_16x16x32_bf16 v[0:3], v[186:189], v[218:221], v[0:3]
	v_mfma_f32_16x16x32_bf16 v[52:55], v[178:181], v[198:201], v[52:55]
	v_mfma_f32_16x16x32_bf16 v[48:51], v[190:193], v[198:201], v[48:51]
	v_mfma_f32_16x16x32_bf16 v[36:39], v[178:181], v[206:209], v[36:39]
	v_mfma_f32_16x16x32_bf16 v[32:35], v[190:193], v[206:209], v[32:35]
	v_mfma_f32_16x16x32_bf16 v[20:23], v[178:181], v[214:217], v[20:23]
	v_mfma_f32_16x16x32_bf16 v[16:19], v[190:193], v[214:217], v[16:19]
	v_mfma_f32_16x16x32_bf16 v[4:7], v[178:181], v[222:225], v[4:7]
	v_mfma_f32_16x16x32_bf16 v[0:3], v[190:193], v[222:225], v[0:3]
	s_setprio 0
	s_barrier
	s_add_i32 s43, 0, 0x18000
	s_add_i32 s44, 0, 0x1c000
	v_add_u32_e32 v140, s43, v182
	v_add_u32_e32 v152, s44, v182
	ds_read_b128 v[128:131], v140
	ds_read_b128 v[132:135], v140 offset:1024
	ds_read_b128 v[136:139], v140 offset:2048
	ds_read_b128 v[140:143], v140 offset:3072
	ds_read_b128 v[174:177], v152
	ds_read_b128 v[178:181], v152 offset:1024
	ds_read_b128 v[186:189], v152 offset:2048
	ds_read_b128 v[190:193], v152 offset:3072
	s_add_u32 s8, s8, 0x40000
	s_addc_u32 s9, s9, 0
	s_mov_b32 m0, s31
	ds_read_b128 v[194:197], v185 offset:32768
	ds_read_b128 v[198:201], v185 offset:33792
	ds_read_b128 v[202:205], v185 offset:34816
	ds_read_b128 v[206:209], v185 offset:35840
	ds_read_b128 v[210:213], v185 offset:36864
	ds_read_b128 v[214:217], v185 offset:37888
	ds_read_b128 v[218:221], v185 offset:38912
	ds_read_b128 v[222:225], v185 offset:39936
	global_load_lds_dwordx4 v150, s[8:9]
	s_mov_b32 m0, s34
	s_nop 0
	global_load_lds_dwordx4 v146, s[8:9]
	s_waitcnt vmcnt(8)
	s_waitcnt lgkmcnt(0)
	s_barrier
	s_setprio 1
	s_waitcnt lgkmcnt(0)
	v_mfma_f32_16x16x32_bf16 v[124:127], v[128:131], v[194:197], v[124:127]
	v_mfma_f32_16x16x32_bf16 v[120:123], v[136:139], v[194:197], v[120:123]
	v_mfma_f32_16x16x32_bf16 v[108:111], v[128:131], v[202:205], v[108:111]
	v_mfma_f32_16x16x32_bf16 v[104:107], v[136:139], v[202:205], v[104:107]
	v_mfma_f32_16x16x32_bf16 v[92:95], v[128:131], v[210:213], v[92:95]
	v_mfma_f32_16x16x32_bf16 v[88:91], v[136:139], v[210:213], v[88:91]
	v_mfma_f32_16x16x32_bf16 v[76:79], v[128:131], v[218:221], v[76:79]
	v_mfma_f32_16x16x32_bf16 v[72:75], v[136:139], v[218:221], v[72:75]
	v_mfma_f32_16x16x32_bf16 v[124:127], v[132:135], v[198:201], v[124:127]
	v_mfma_f32_16x16x32_bf16 v[120:123], v[140:143], v[198:201], v[120:123]
	v_mfma_f32_16x16x32_bf16 v[108:111], v[132:135], v[206:209], v[108:111]
	v_mfma_f32_16x16x32_bf16 v[104:107], v[140:143], v[206:209], v[104:107]
	v_mfma_f32_16x16x32_bf16 v[92:95], v[132:135], v[214:217], v[92:95]
	v_mfma_f32_16x16x32_bf16 v[88:91], v[140:143], v[214:217], v[88:91]
	v_mfma_f32_16x16x32_bf16 v[76:79], v[132:135], v[222:225], v[76:79]
	v_mfma_f32_16x16x32_bf16 v[72:75], v[140:143], v[222:225], v[72:75]
	s_setprio 0
	s_setprio 1
	v_mfma_f32_16x16x32_bf16 v[116:119], v[174:177], v[194:197], v[116:119]
	v_mfma_f32_16x16x32_bf16 v[112:115], v[186:189], v[194:197], v[112:115]
	v_mfma_f32_16x16x32_bf16 v[100:103], v[174:177], v[202:205], v[100:103]
	v_mfma_f32_16x16x32_bf16 v[96:99], v[186:189], v[202:205], v[96:99]
	v_mfma_f32_16x16x32_bf16 v[84:87], v[174:177], v[210:213], v[84:87]
	v_mfma_f32_16x16x32_bf16 v[80:83], v[186:189], v[210:213], v[80:83]
	v_mfma_f32_16x16x32_bf16 v[68:71], v[174:177], v[218:221], v[68:71]
	v_mfma_f32_16x16x32_bf16 v[64:67], v[186:189], v[218:221], v[64:67]
	v_mfma_f32_16x16x32_bf16 v[116:119], v[178:181], v[198:201], v[116:119]
	v_mfma_f32_16x16x32_bf16 v[112:115], v[190:193], v[198:201], v[112:115]
	v_mfma_f32_16x16x32_bf16 v[100:103], v[178:181], v[206:209], v[100:103]
	v_mfma_f32_16x16x32_bf16 v[96:99], v[190:193], v[206:209], v[96:99]
	v_mfma_f32_16x16x32_bf16 v[84:87], v[178:181], v[214:217], v[84:87]
	v_mfma_f32_16x16x32_bf16 v[80:83], v[190:193], v[214:217], v[80:83]
	v_mfma_f32_16x16x32_bf16 v[68:71], v[178:181], v[222:225], v[68:71]
	v_mfma_f32_16x16x32_bf16 v[64:67], v[190:193], v[222:225], v[64:67]
	s_setprio 0
	s_barrier
; #define PG8_STAGE(bufoff, gbase, voff) do { _Pragma("unroll") for (int _i = 0; _i < 2; ++_i) \
;         __builtin_amdgcn_global_load_lds((const unsigned*)((const char*)(gbase) + (voff)[_i]), (PG8_LAS unsigned*)(lds + (bufoff) + ldsw + _i * 8192), 16, 0, 0); } while (0)
; #define PG8_LDA(dst, b, h) do { _Pragma("unroll") for (int m = 0; m < 4; ++m) _Pragma("unroll") for (int k = 0; k < 2; ++k) dst[m][k] = *(const PG8_LAS bf16x8*)(lds + PG8_SA(b, h) + aoff + m * 2048 + k * 1024); } while (0)
; #define PG8_MMA(ai, bj, At, Bt) do { __builtin_amdgcn_s_setprio(1); _Pragma("unroll") for (int m = 0; m < 4; ++m) _Pragma("unroll") for (int n = 0; n < 2; ++n) _Pragma("unroll") for (int k = 0; k < 2; ++k) \
;         acc[ai][bj][m][n] = __builtin_amdgcn_mfma_f32_16x16x32_bf16(Bt[n][k], At[m][k], acc[ai][bj][m][n], 0, 0, 0); __builtin_amdgcn_s_setprio(0); } while (0)
; #define PG8_WAIT_V(n) asm volatile("s_waitcnt vmcnt(" #n ")" ::: "memory")
; #define PG8_WAIT_L(n) asm volatile("s_waitcnt lgkmcnt(" #n ")" ::: "memory")
; #define PG8_BAR __builtin_amdgcn_s_barrier()
; #define PG8_SCHED __builtin_amdgcn_sched_barrier(0)
; template <class Epi, class Sched, bool ALIGN_EPI = false, bool SP2 = false>
; __device__ __forceinline__ void gemm_phase(PG8_LAS unsigned char* lds, const Gemm g, const Sched& S, const Epi& E) {
;     ...
;         for (int t = 0; t < nt; t += 2) {
;     ...
;             PG8_LDA(At, 1, 1); PG8_STAGE(PG8_SB(1, 0), b3, voffB); PG8_STAGE(PG8_SB(1, 1), b3 + hstep, voffB); PG8_STAGE(PG8_SA(1, 0), a3, voffA);
;             PG8_WAIT_V(8); PG8_WAIT_L(0); PG8_BAR; PG8_MMA(1, 0, At, B0); PG8_MMA(1, 1, At, B1); PG8_BAR; PG8_SCHED;
	s_add_i32 s8, s43, s28
	v_lshl_add_u64 v[226:227], v[226:227], 0, s[94:95]
	s_mov_b32 m0, s8
	ds_read_b128 v[194:197], v185 offset:49152
	ds_read_b128 v[198:201], v185 offset:50176
	ds_read_b128 v[202:205], v185 offset:51200
	ds_read_b128 v[206:209], v185 offset:52224
	ds_read_b128 v[210:213], v185 offset:53248
	ds_read_b128 v[214:217], v185 offset:54272
	ds_read_b128 v[218:221], v185 offset:55296
	ds_read_b128 v[222:225], v185 offset:56320
	global_load_lds_dwordx4 v[226:227], off
	s_add_i32 m0, s8, 0x2000
	s_add_u32 s2, s2, 0x40080
	v_lshl_add_u64 v[226:227], v[228:229], 0, s[94:95]
	s_addc_u32 s3, s3, 0
	s_add_i32 s8, s44, s28
	global_load_lds_dwordx4 v[226:227], off
	s_mov_b32 m0, s8
	s_nop 0
	global_load_lds_dwordx4 v148, s[2:3]
	s_add_i32 m0, s8, 0x2000
	s_nop 0
	global_load_lds_dwordx4 v144, s[2:3]
	v_lshl_add_u64 v[226:227], v[230:231], 0, s[94:95]
	s_mov_b32 m0, s36
	s_nop 0
	global_load_lds_dwordx4 v[226:227], off
	v_lshl_add_u64 v[226:227], v[232:233], 0, s[94:95]
	s_mov_b32 m0, s37
	s_nop 0
	global_load_lds_dwordx4 v[226:227], off
	s_waitcnt vmcnt(8)
	s_waitcnt lgkmcnt(0)
	s_barrier
	s_setprio 1
	s_waitcnt lgkmcnt(0)
	v_mfma_f32_16x16x32_bf16 v[60:63], v[128:131], v[194:197], v[60:63]
	v_mfma_f32_16x16x32_bf16 v[56:59], v[136:139], v[194:197], v[56:59]
	v_mfma_f32_16x16x32_bf16 v[44:47], v[128:131], v[202:205], v[44:47]
	v_mfma_f32_16x16x32_bf16 v[40:43], v[136:139], v[202:205], v[40:43]
	v_mfma_f32_16x16x32_bf16 v[28:31], v[128:131], v[210:213], v[28:31]
	v_mfma_f32_16x16x32_bf16 v[24:27], v[136:139], v[210:213], v[24:27]
	v_mfma_f32_16x16x32_bf16 v[12:15], v[128:131], v[218:221], v[12:15]
	v_mfma_f32_16x16x32_bf16 v[8:11], v[136:139], v[218:221], v[8:11]
	v_mfma_f32_16x16x32_bf16 v[60:63], v[132:135], v[198:201], v[60:63]
	v_mfma_f32_16x16x32_bf16 v[56:59], v[140:143], v[198:201], v[56:59]
	v_mfma_f32_16x16x32_bf16 v[44:47], v[132:135], v[206:209], v[44:47]
	v_mfma_f32_16x16x32_bf16 v[40:43], v[140:143], v[206:209], v[40:43]
	v_mfma_f32_16x16x32_bf16 v[28:31], v[132:135], v[214:217], v[28:31]
	v_mfma_f32_16x16x32_bf16 v[24:27], v[140:143], v[214:217], v[24:27]
	v_mfma_f32_16x16x32_bf16 v[12:15], v[132:135], v[222:225], v[12:15]
	v_mfma_f32_16x16x32_bf16 v[8:11], v[140:143], v[222:225], v[8:11]
	s_setprio 0
	s_setprio 1
	v_mfma_f32_16x16x32_bf16 v[52:55], v[174:177], v[194:197], v[52:55]
	v_mfma_f32_16x16x32_bf16 v[48:51], v[186:189], v[194:197], v[48:51]
	v_mfma_f32_16x16x32_bf16 v[36:39], v[174:177], v[202:205], v[36:39]
	v_mfma_f32_16x16x32_bf16 v[32:35], v[186:189], v[202:205], v[32:35]
	v_mfma_f32_16x16x32_bf16 v[20:23], v[174:177], v[210:213], v[20:23]
	v_mfma_f32_16x16x32_bf16 v[16:19], v[186:189], v[210:213], v[16:19]
	v_mfma_f32_16x16x32_bf16 v[4:7], v[174:177], v[218:221], v[4:7]
	v_mfma_f32_16x16x32_bf16 v[0:3], v[186:189], v[218:221], v[0:3]
	v_mfma_f32_16x16x32_bf16 v[52:55], v[178:181], v[198:201], v[52:55]
	v_mfma_f32_16x16x32_bf16 v[48:51], v[190:193], v[198:201], v[48:51]
	v_mfma_f32_16x16x32_bf16 v[36:39], v[178:181], v[206:209], v[36:39]
	v_mfma_f32_16x16x32_bf16 v[32:35], v[190:193], v[206:209], v[32:35]
	v_mfma_f32_16x16x32_bf16 v[20:23], v[178:181], v[214:217], v[20:23]
	v_mfma_f32_16x16x32_bf16 v[16:19], v[190:193], v[214:217], v[16:19]
	v_mfma_f32_16x16x32_bf16 v[4:7], v[178:181], v[222:225], v[4:7]
	v_mfma_f32_16x16x32_bf16 v[0:3], v[190:193], v[222:225], v[0:3]
	s_setprio 0
	s_barrier
	s_add_i32 s42, s42, 2
	s_add_u32 s0, s0, 0x100
	s_addc_u32 s1, s1, 0
	s_add_u32 s21, s21, 0x100
	s_addc_u32 s33, s33, 0
	s_cmp_gt_u32 s42, 13
	s_cbranch_scc0 .LBB0_116
	s_and_b64 vcc, exec, s[16:17]
	s_cbranch_vccz .LBB0_119
	s_barrier
